# S5 pass 0: the 16 chunk operand loads of a wave issued up front as direct HBM-to-LDS loads into its (idle in pass 0) scan buffer, consumed with counted vmcnt waits; plus XCD-local batch/group assignme
# speedup vs baseline: 1.0055x; 1.0050x over previous
; DI unsigned pack2(float a, float b) { f2_t v = {a, b}; bf2_t r = __builtin_convertvector(v, bf2_t); return __builtin_bit_cast(unsigned, r); }
; DI void mix_s5(WVP CP pp, int l, u16* __restrict__ proj, char* smem) {
;     ...
;     float lr, li;
;     { float ar = a_re[lane], ai = a_im[lane]; float mg = expf(ar * dt); float sn, cs; sincosf(ai * dt, &sn, &cs); lr = mg * cs; li = mg * sn; }
;     bf16x8 bfrag[4];
;     float lam_r[2], lam_i[2];
;     for (int half = 0; half < 2; ++half) {
;       int ps = 32 * half + l31;
;       float ar = a_re[ps], ai = a_im[ps]; float mg = expf(ar * dt); float sn, cs; sincosf(ai * dt, &sn, &cs);
;       lam_r[half] = mg * cs; lam_i[half] = mg * sn;
;       float xr = mg * cs - 1.f, xi = mg * sn, den = 1.f / (ar * ar + ai * ai);
;       float cr = (xr * ar + xi * ai) * den, ci = (xi * ar - xr * ai) * den;
;       float vr[8], vi[8];
;       for (int j = 0; j < 8; ++j) { float br = b_re[ps * 16 + 8 * h + j], bi = b_im[ps * 16 + 8 * h + j]; vr[j] = cr * br - ci * bi; vi[j] = cr * bi + ci * br; }
;       uint4 a = {pack2(vr[0], vr[1]), pack2(vr[2], vr[3]), pack2(vr[4], vr[5]), pack2(vr[6], vr[7])};
;       uint4 c = {pack2(vi[0], vi[1]), pack2(vi[2], vi[3]), pack2(vi[4], vi[5]), pack2(vi[6], vi[7])};
;       bfrag[half] = __builtin_bit_cast(bf16x8, a); bfrag[2 + half] = __builtin_bit_cast(bf16x8, c);
;     }
;     bf16x8 cfrag[4];
;     { int c = lane & 15, kq = lane >> 4;
;       for (int s = 0; s < 4; ++s) {
;         float v[8];
;         for (int j = 0; j < 8; ++j) { int k = 32 * s + 8 * kq + j; v[j] = k < 64 ? c_re[c * 64 + k] : -c_im[c * 64 + k - 64]; }
;         uint4 a = {pack2(v[0], v[1]), pack2(v[2], v[3]), pack2(v[4], v[5]), pack2(v[6], v[7])};
;         cfrag[s] = __builtin_bit_cast(bf16x8, a);
;       } }
;     const float dskip = dsk[lane & 15];
.LBB0_296:
	s_or_b64 exec, exec, s[10:11]
	v_mul_f32_e32 v28, v25, v20
	v_mul_f32_e32 v33, 0x3fb8aa3b, v28
	s_mov_b32 s1, 0x3fb8aa3b
	v_fma_f32 v34, v28, s1, -v33
	v_rndne_f32_e32 v35, v33
	v_fmac_f32_e32 v34, 0x32a5705f, v28
	v_sub_f32_e32 v33, v33, v35
	v_add_f32_e32 v33, v33, v34
	v_cvt_i32_f32_e32 v34, v35
	v_exp_f32_e32 v33, v33
	s_mov_b32 s12, 0xc2ce8ed0
	v_cmp_ngt_f32_e32 vcc, s12, v28
	s_mov_b32 s13, 0x42b17218
	v_ldexp_f32 v33, v33, v34
	v_cndmask_b32_e32 v33, 0, v33, vcc
	v_cmp_nlt_f32_e32 vcc, s13, v28
	v_mov_b32_e32 v44, 0x7f800000
	v_mov_b32_e32 v42, 0x3c0881c4
	v_cndmask_b32_e32 v28, v44, v33, vcc
	v_mul_f32_e32 v33, v29, v29
	v_fmamk_f32 v34, v33, 0xb94c1982, v42
	v_fmaak_f32 v34, v33, v34, 0xbe2aaa9d
	v_mul_f32_e32 v34, v33, v34
	v_mov_b32_e32 v43, 0xbab64f3b
	v_fmac_f32_e32 v29, v29, v34
	v_fmamk_f32 v34, v33, 0x37d75334, v43
	v_fmaak_f32 v34, v33, v34, 0x3d2aabf7
	v_fmaak_f32 v34, v33, v34, 0xbf000004
	v_fma_f32 v33, v33, v34, 1.0
	v_lshlrev_b32_e32 v34, 30, v32
	v_and_b32_e32 v32, 1, v32
	v_cmp_eq_u32_e32 vcc, 0, v32
	v_xor_b32_e32 v23, v23, v22
	v_and_b32_e32 v35, 0x80000000, v34
	v_cndmask_b32_e32 v32, v33, v29, vcc
	v_xor_b32_e32 v23, v23, v32
	v_xor_b32_e32 v32, v23, v35
	v_xor_b32_e32 v23, 0x80000000, v29
	v_cndmask_b32_e32 v23, v23, v33, vcc
	s_brev_b32 s26, 1
	s_movk_i32 s27, 0x1f8
	v_bitop3_b32 v23, v23, v34, s26 bitop3:0x78
	v_cmp_class_f32_e64 vcc, v22, s27
	v_mov_b32_e32 v45, 0x7fc00000
	s_lshl_b64 s[14:15], s[14:15], 2
	v_cndmask_b32_e32 v29, v45, v23, vcc
	v_pk_mul_f32 v[22:23], v[20:21], v[20:21]
	v_mul_f32_e32 v221, v24, v25
	v_add_f32_e32 v23, v22, v23
	v_div_scale_f32 v33, s[10:11], v23, v23, 1.0
	v_rcp_f32_e32 v34, v33
	v_cndmask_b32_e32 v22, v45, v32, vcc
	v_mul_f32_e32 v22, v28, v22
	v_fma_f32 v32, v28, v29, -1.0
	v_fma_f32 v35, -v33, v34, 1.0
	v_fmac_f32_e32 v34, v35, v34
	v_div_scale_f32 v35, vcc, 1.0, v23, 1.0
	v_mul_f32_e32 v36, v35, v34
	v_fma_f32 v37, -v33, v36, v35
	v_fmac_f32_e32 v36, v37, v34
	v_fma_f32 v33, -v33, v36, v35
	v_div_fmas_f32 v33, v33, v34, v36
	v_div_fixup_f32 v36, v33, v23, 1.0
	v_mov_b32_e32 v33, v22
	v_pk_mul_f32 v[34:35], v[20:21], v[32:33]
	s_mov_b32 s40, 0x3fb8aa3b
	v_add_f32_e32 v23, v34, v35
	v_mul_f32_e32 v34, v36, v23
	v_mov_b32_e32 v23, v32
	v_pk_mul_f32 v[20:21], v[20:21], v[22:23]
	s_waitcnt vmcnt(1)
	v_pk_mul_f32 v[32:33], v[14:15], v[34:35] op_sel_hi:[1,0]
	v_sub_f32_e32 v20, v20, v21
	v_mul_f32_e32 v20, v36, v20
	v_pk_mul_f32 v[14:15], v[14:15], v[20:21] op_sel_hi:[1,0]
	v_pk_fma_f32 v[32:33], v[10:11], v[20:21], v[32:33] op_sel_hi:[1,0,1]
	v_pk_fma_f32 v[10:11], v[10:11], v[34:35], v[14:15] op_sel_hi:[1,0,1] neg_lo:[0,0,1] neg_hi:[0,0,1]
	v_pk_mul_f32 v[14:15], v[16:17], v[34:35] op_sel_hi:[1,0]
	v_cvt_pk_bf16_f32 v66, v10, v11
	v_pk_fma_f32 v[36:37], v[12:13], v[20:21], v[14:15] op_sel_hi:[1,0,1]
	v_pk_mul_f32 v[14:15], v[16:17], v[20:21] op_sel_hi:[1,0]
	v_cvt_pk_bf16_f32 v70, v32, v33
	v_pk_fma_f32 v[12:13], v[12:13], v[34:35], v[14:15] op_sel_hi:[1,0,1] neg_lo:[0,0,1] neg_hi:[0,0,1]
	v_pk_mul_f32 v[14:15], v[6:7], v[34:35] op_sel_hi:[1,0]
	v_pk_mul_f32 v[6:7], v[6:7], v[20:21] op_sel_hi:[1,0]
	v_pk_fma_f32 v[38:39], v[2:3], v[20:21], v[14:15] op_sel_hi:[1,0,1]
	v_pk_fma_f32 v[2:3], v[2:3], v[34:35], v[6:7] op_sel_hi:[1,0,1] neg_lo:[0,0,1] neg_hi:[0,0,1]
	v_pk_mul_f32 v[6:7], v[34:35], v[8:9] op_sel_hi:[0,1]
	v_pk_fma_f32 v[40:41], v[4:5], v[20:21], v[6:7] op_sel_hi:[1,0,1]
	v_pk_mul_f32 v[6:7], v[20:21], v[8:9] op_sel_hi:[0,1]
	v_cvt_pk_bf16_f32 v68, v2, v3
	s_waitcnt vmcnt(0)
	v_mul_f32_e32 v2, v25, v18
	v_pk_fma_f32 v[4:5], v[4:5], v[34:35], v[6:7] op_sel_hi:[1,0,1] neg_lo:[0,0,1] neg_hi:[0,0,1]
	v_mul_f32_e32 v3, 0x3fb8aa3b, v2
	v_cvt_pk_bf16_f32 v69, v4, v5
	v_fma_f32 v4, v2, s1, -v3
	v_rndne_f32_e32 v5, v3
	v_fmac_f32_e32 v4, 0x32a5705f, v2
	v_sub_f32_e32 v3, v3, v5
	v_add_f32_e32 v3, v3, v4
	v_exp_f32_e32 v3, v3
	v_cvt_i32_f32_e32 v4, v5
	v_cmp_ngt_f32_e32 vcc, s12, v2
	v_lshlrev_b32_e32 v20, 30, v31
	v_xor_b32_e32 v21, v27, v26
	v_ldexp_f32 v3, v3, v4
	v_cndmask_b32_e32 v3, 0, v3, vcc
	v_cmp_nlt_f32_e32 vcc, s13, v2
	v_mul_f32_e32 v2, v30, v30
	v_cvt_pk_bf16_f32 v67, v12, v13
	v_cndmask_b32_e32 v4, v44, v3, vcc
	v_fmamk_f32 v3, v2, 0xb94c1982, v42
	v_fmaak_f32 v3, v2, v3, 0xbe2aaa9d
	v_mul_f32_e32 v3, v2, v3
	v_fmac_f32_e32 v30, v30, v3
	v_fmamk_f32 v3, v2, 0x37d75334, v43
	v_fmaak_f32 v3, v2, v3, 0x3d2aabf7
	v_fmaak_f32 v3, v2, v3, 0xbf000004
	v_fma_f32 v5, v2, v3, 1.0
	v_and_b32_e32 v3, 1, v31
	v_cmp_eq_u32_e32 vcc, 0, v3
	v_and_b32_e32 v2, 0x80000000, v20
	global_load_dwordx4 v[6:9], v193, s[38:39] offset:16
	global_load_dwordx4 v[10:13], v193, s[38:39]
	global_load_dwordx4 v[14:17], v193, s[28:29] offset:16
	global_load_dwordx4 v[32:35], v193, s[28:29]
	v_cndmask_b32_e32 v3, v5, v30, vcc
	v_xor_b32_e32 v3, v21, v3
	v_xor_b32_e32 v21, v3, v2
	v_lshl_add_u64 v[2:3], v[122:123], 0, s[14:15]
	global_load_dwordx4 v[98:101], v[2:3], off offset:16
	global_load_dwordx4 v[110:113], v[2:3], off
	global_load_dwordx4 v[90:93], v[2:3], off offset:144
	global_load_dwordx4 v[106:109], v[2:3], off offset:128
	v_lshl_add_u64 v[2:3], v[124:125], 0, s[14:15]
	global_load_dwordx4 v[86:89], v[2:3], off offset:16
	global_load_dwordx4 v[102:105], v[2:3], off
	global_load_dwordx4 v[82:85], v[2:3], off offset:144
	global_load_dwordx4 v[94:97], v[2:3], off offset:128
	s_lshl_b32 s14, s0, 6
	s_mov_b32 s15, s59
	v_lshl_add_u64 v[2:3], v[118:119], 0, s[14:15]
	global_load_dword v216, v[2:3], off
	v_xor_b32_e32 v23, 0x80000000, v30
	v_cndmask_b32_e32 v2, v23, v5, vcc
	v_bitop3_b32 v2, v2, v20, s26 bitop3:0x78
	v_cmp_class_f32_e64 vcc, v26, s27
	s_ashr_i32 s28, s46, 5
; DI unsigned pack2(float a, float b) { f2_t v = {a, b}; bf2_t r = __builtin_convertvector(v, bf2_t); return __builtin_bit_cast(unsigned, r); }
; DI void mix_s5(WVP CP pp, int l, u16* __restrict__ proj, char* smem) {
;     ...
;       float ar = a_re[ps], ai = a_im[ps]; float mg = expf(ar * dt); float sn, cs; sincosf(ai * dt, &sn, &cs);
;       lam_r[half] = mg * cs; lam_i[half] = mg * sn;
;       float xr = mg * cs - 1.f, xi = mg * sn, den = 1.f / (ar * ar + ai * ai);
;       float cr = (xr * ar + xi * ai) * den, ci = (xi * ar - xr * ai) * den;
;       float vr[8], vi[8];
;       for (int j = 0; j < 8; ++j) { float br = b_re[ps * 16 + 8 * h + j], bi = b_im[ps * 16 + 8 * h + j]; vr[j] = cr * br - ci * bi; vi[j] = cr * bi + ci * br; }
;       uint4 a = {pack2(vr[0], vr[1]), pack2(vr[2], vr[3]), pack2(vr[4], vr[5]), pack2(vr[6], vr[7])};
;       uint4 c = {pack2(vi[0], vi[1]), pack2(vi[2], vi[3]), pack2(vi[4], vi[5]), pack2(vi[6], vi[7])};
;       bfrag[half] = __builtin_bit_cast(bf16x8, a); bfrag[2 + half] = __builtin_bit_cast(bf16x8, c);
;     }
;     ...
;       for (int half = 0; half < 2; ++half) {
;         const float ar = lam_r[half], ai = lam_i[half];
;         const float l2r = ar * ar - ai * ai, l2i = 2.f * ar * ai;
;         const float l4r = l2r * l2r - l2i * l2i, l4i = 2.f * l2r * l2i;
;         const float l5r = l4r * ar - l4i * ai, l5i = l4r * ai + l4i * ar;
;         const float l8r = l4r * l4r - l4i * l4i, l8i = 2.f * l4r * l4i;
;         const float l16r = l8r * l8r - l8i * l8i, l16i = 2.f * l8r * l8i;
;         l32r[half] = l16r * l16r - l16i * l16i; l32i[half] = 2.f * l16r * l16i;
;         float cr = h ? 1.f : l4r, ci = h ? 0.f : l4i;
; #pragma unroll
;         for (int i = 15; i >= 0; --i) {
;           wre[half][i] = cr; wim[half][i] = ci;
;           const float mr = (i & 3) ? ar : l5r, mi = (i & 3) ? ai : l5i;
;           const float nr = cr * mr - ci * mi, ni = cr * mi + ci * mr; cr = nr; ci = ni;
;         }
;       }
	s_and_b32 s1, s4, 31
	v_cndmask_b32_e32 v5, v45, v2, vcc
	v_pk_mul_f32 v[2:3], v[18:19], v[18:19]
	s_ashr_i32 s29, s28, 31
	v_add_f32_e32 v20, v2, v3
	v_div_scale_f32 v23, s[14:15], v20, v20, 1.0
	v_rcp_f32_e32 v24, v23
	v_cndmask_b32_e32 v2, v45, v21, vcc
	s_lshl_b32 s58, s1, 5
	s_lshl_b64 s[14:15], s[28:29], 12
	v_fma_f32 v21, -v23, v24, 1.0
	v_fmac_f32_e32 v24, v21, v24
	v_div_scale_f32 v21, vcc, 1.0, v20, 1.0
	v_mul_f32_e32 v25, v21, v24
	v_fma_f32 v26, -v23, v25, v21
	v_fmac_f32_e32 v25, v26, v24
	s_add_u32 s1, s14, s44
	v_mul_f32_e32 v3, v4, v2
	v_fma_f32 v2, v4, v5, -1.0
	v_fma_f32 v21, -v23, v25, v21
	s_addc_u32 s14, s15, s45
	v_div_fmas_f32 v21, v21, v24, v25
	v_mov_b32_e32 v24, v3
	v_mov_b32_e32 v25, v2
	s_mulk_i32 s14, 0x2600
	s_mul_hi_u32 s15, s1, 0x2600
	v_div_fixup_f32 v23, v21, v20, 1.0
	v_pk_mul_f32 v[20:21], v[18:19], v[2:3]
	v_pk_mul_f32 v[18:19], v[18:19], v[24:25]
	s_add_i32 s15, s15, s14
	s_mulk_i32 s1, 0x2600
	v_add_f32_e32 v20, v20, v21
	v_sub_f32_e32 v2, v18, v19
	s_add_u32 s1, s54, s1
	v_mul_f32_e32 v20, v23, v20
	v_mul_f32_e32 v2, v23, v2
	s_addc_u32 s14, s55, s15
	s_lshl_b32 s0, s0, 5
	s_add_u32 s0, s1, s0
	s_addc_u32 s1, s14, 0
	s_add_u32 s26, s0, 0x2200
	v_cvt_pk_bf16_f32 v71, v36, v37
	v_cvt_pk_bf16_f32 v72, v38, v39
	v_cvt_pk_bf16_f32 v73, v40, v41
	v_mov_b32_e32 v200, 0x7f800000
	v_cmp_ngt_f32_e64 s[10:11], s12, v221
	v_cmp_nlt_f32_e64 s[12:13], s13, v221
	v_mov_b32_e32 v198, 0x3c0881c4
	v_mov_b32_e32 v199, 0xbab64f3b
	s_brev_b32 s38, 1
	s_addc_u32 s27, s1, 0
	s_andn2_b64 vcc, exec, s[30:31]
	v_lshlrev_b32_e32 v148, 1, v120
	s_mul_hi_i32 s15, s28, 0x2600000
	s_mul_i32 s14, s28, 0x2600000
	s_barrier
	s_waitcnt vmcnt(12)
	v_pk_mul_f32 v[26:27], v[6:7], v[20:21] op_sel_hi:[1,0]
	v_pk_mul_f32 v[6:7], v[6:7], v[2:3] op_sel_hi:[1,0]
	s_waitcnt vmcnt(11)
	v_pk_mul_f32 v[18:19], v[10:11], v[20:21] op_sel_hi:[1,0]
	v_pk_mul_f32 v[10:11], v[10:11], v[2:3] op_sel_hi:[1,0]
	v_pk_mul_f32 v[24:25], v[12:13], v[20:21] op_sel_hi:[1,0]
	v_pk_mul_f32 v[12:13], v[12:13], v[2:3] op_sel_hi:[1,0]
	s_waitcnt vmcnt(10)
	v_pk_fma_f32 v[26:27], v[14:15], v[2:3], v[26:27] op_sel_hi:[1,0,1]
	v_pk_fma_f32 v[6:7], v[14:15], v[20:21], v[6:7] op_sel_hi:[1,0,1] neg_lo:[0,0,1] neg_hi:[0,0,1]
	v_pk_mul_f32 v[14:15], v[20:21], v[8:9] op_sel_hi:[0,1]
	v_pk_mul_f32 v[8:9], v[2:3], v[8:9] op_sel_hi:[0,1]
	s_waitcnt vmcnt(9)
	v_pk_fma_f32 v[18:19], v[32:33], v[2:3], v[18:19] op_sel_hi:[1,0,1]
	v_pk_fma_f32 v[10:11], v[32:33], v[20:21], v[10:11] op_sel_hi:[1,0,1] neg_lo:[0,0,1] neg_hi:[0,0,1]
	v_pk_fma_f32 v[24:25], v[34:35], v[2:3], v[24:25] op_sel_hi:[1,0,1]
	v_pk_fma_f32 v[12:13], v[34:35], v[20:21], v[12:13] op_sel_hi:[1,0,1] neg_lo:[0,0,1] neg_hi:[0,0,1]
	v_pk_fma_f32 v[14:15], v[16:17], v[2:3], v[14:15] op_sel_hi:[1,0,1]
	v_pk_fma_f32 v[8:9], v[16:17], v[20:21], v[8:9] op_sel_hi:[1,0,1] neg_lo:[0,0,1] neg_hi:[0,0,1]
	v_cvt_pk_bf16_f32 v74, v10, v11
	v_cvt_pk_bf16_f32 v75, v12, v13
	v_cvt_pk_bf16_f32 v76, v6, v7
	v_cvt_pk_bf16_f32 v77, v8, v9
	v_cvt_pk_bf16_f32 v78, v18, v19
	v_cvt_pk_bf16_f32 v79, v24, v25
	v_cvt_pk_bf16_f32 v80, v26, v27
	v_cvt_pk_bf16_f32 v81, v14, v15
	s_cbranch_vccnz .LBB0_304
	v_mul_f32_e32 v6, v28, v29
	v_mul_f32_e32 v7, v4, v5
	v_mov_b32_e32 v23, v3
	v_pk_add_f32 v[8:9], v[6:7], v[6:7]
	v_pk_mul_f32 v[4:5], v[22:23], v[22:23]
	v_pk_mul_f32 v[8:9], v[8:9], v[22:23]
	v_pk_fma_f32 v[4:5], v[6:7], v[6:7], v[4:5] neg_lo:[0,0,1] neg_hi:[0,0,1]
	v_pk_mul_f32 v[10:11], v[8:9], v[8:9]
	v_mov_b32_e32 v149, v1
	v_pk_fma_f32 v[10:11], v[4:5], v[4:5], v[10:11] neg_lo:[0,0,1] neg_hi:[0,0,1]
	v_pk_add_f32 v[4:5], v[4:5], v[4:5]
	v_pk_add_f32 v[12:13], v[10:11], v[10:11]
	v_pk_mul_f32 v[4:5], v[8:9], v[4:5]
	v_cndmask_b32_e64 v153, 1.0, v11, s[8:9]
	v_pk_mul_f32 v[8:9], v[4:5], v[4:5]
	v_pk_mul_f32 v[12:13], v[4:5], v[12:13]
	v_cndmask_b32_e64 v155, 0, v5, s[8:9]
	v_cndmask_b32_e64 v154, 0, v4, s[8:9]
	v_pk_mul_f32 v[18:19], v[22:23], v[4:5]
	v_pk_mul_f32 v[4:5], v[6:7], v[4:5]
	v_pk_fma_f32 v[8:9], v[10:11], v[10:11], v[8:9] neg_lo:[0,0,1] neg_hi:[0,0,1]
	v_cndmask_b32_e64 v152, 1.0, v10, s[8:9]
	v_pk_fma_f32 v[18:19], v[6:7], v[10:11], v[18:19] neg_lo:[0,0,1] neg_hi:[0,0,1]
	v_pk_fma_f32 v[4:5], v[22:23], v[10:11], v[4:5]
	v_pk_mul_f32 v[10:11], v[22:23], v[154:155]
	v_mov_b32_e32 v147, v1
	v_pk_fma_f32 v[156:157], v[6:7], v[152:153], v[10:11] neg_lo:[0,0,1] neg_hi:[0,0,1]
	v_pk_mul_f32 v[10:11], v[6:7], v[154:155]
	v_pk_mul_f32 v[14:15], v[12:13], v[12:13]
	v_pk_fma_f32 v[158:159], v[22:23], v[152:153], v[10:11]
	v_pk_fma_f32 v[14:15], v[8:9], v[8:9], v[14:15] neg_lo:[0,0,1] neg_hi:[0,0,1]
	v_pk_mul_f32 v[10:11], v[22:23], v[158:159]
	v_pk_add_f32 v[8:9], v[8:9], v[8:9]
	v_pk_fma_f32 v[160:161], v[6:7], v[156:157], v[10:11] neg_lo:[0,0,1] neg_hi:[0,0,1]
	v_pk_mul_f32 v[10:11], v[6:7], v[158:159]
	v_pk_mul_f32 v[8:9], v[12:13], v[8:9]
	v_pk_fma_f32 v[162:163], v[22:23], v[156:157], v[10:11]
	v_pk_mul_f32 v[12:13], v[8:9], v[8:9]
	v_pk_mul_f32 v[10:11], v[22:23], v[162:163]
	v_pk_add_f32 v[16:17], v[14:15], v[14:15]
	v_pk_fma_f32 v[164:165], v[6:7], v[160:161], v[10:11] neg_lo:[0,0,1] neg_hi:[0,0,1]
	v_pk_mul_f32 v[10:11], v[6:7], v[162:163]
	v_mov_b32_e32 v150, 0
	v_pk_fma_f32 v[166:167], v[22:23], v[160:161], v[10:11]
	s_or_b64 s[0:1], s[14:15], s[58:59]
	v_pk_mul_f32 v[10:11], v[4:5], v[166:167]
	v_mov_b32_e32 v201, 0x80
	v_pk_fma_f32 v[168:169], v[18:19], v[164:165], v[10:11] neg_lo:[0,0,1] neg_hi:[0,0,1]
	v_pk_mul_f32 v[10:11], v[18:19], v[166:167]
	v_mov_b32_e32 v197, 0x358637bd
	v_pk_fma_f32 v[170:171], v[4:5], v[164:165], v[10:11]
	v_mov_b32_e32 v195, 1
	v_pk_mul_f32 v[10:11], v[22:23], v[170:171]
; DI void mix_s5(WVP CP pp, int l, u16* __restrict__ proj, char* smem) {
;     ...
;         for (int i = 15; i >= 0; --i) {
;           wre[half][i] = cr; wim[half][i] = ci;
;           const float mr = (i & 3) ? ar : l5r, mi = (i & 3) ? ai : l5i;
;           const float nr = cr * mr - ci * mi, ni = cr * mi + ci * mr; cr = nr; ci = ni;
;         }
;       }
;       bf16x8 au_n = *(const bf16x8*)(ub + (long)l31 * INW + 8 * h);
;       f32x16 z; for (int i = 0; i < 16; ++i) z[i] = 0.f;
; #pragma nounroll
;       for (int ch = 0; ch < 16; ++ch) {
;         const bf16x8 au = au_n;
;         if (ch + 1 < 16) au_n = *(const bf16x8*)(ub + (long)((ch + 1) * 32 + l31) * INW + 8 * h);
	v_pk_fma_f32 v[180:181], v[14:15], v[14:15], v[12:13] neg_lo:[0,0,1] neg_hi:[0,0,1]
	v_pk_fma_f32 v[172:173], v[6:7], v[168:169], v[10:11] neg_lo:[0,0,1] neg_hi:[0,0,1]
	v_pk_mul_f32 v[10:11], v[6:7], v[170:171]
	v_pk_mul_f32 v[182:183], v[8:9], v[16:17]
	v_pk_fma_f32 v[174:175], v[22:23], v[168:169], v[10:11]
	v_lshl_add_u64 v[184:185], v[126:127], 0, s[0:1]
	v_mul_f32_e32 v178, v6, v174
	v_mul_f32_e32 v2, v22, v174
	v_fmac_f32_e32 v178, v22, v172
	v_fma_f32 v176, v6, v172, -v2
	v_mul_f32_e32 v223, v6, v178
	v_mul_f32_e32 v2, v22, v178
	v_fmac_f32_e32 v223, v22, v176
	v_fma_f32 v222, v6, v176, -v2
	v_mul_f32_e32 v225, v18, v223
	v_mul_f32_e32 v2, v4, v223
	v_fmac_f32_e32 v225, v4, v222
	v_fma_f32 v224, v18, v222, -v2
	v_mul_f32_e32 v227, v6, v225
	v_mul_f32_e32 v2, v22, v225
	v_fmac_f32_e32 v227, v22, v224
	v_fma_f32 v226, v6, v224, -v2
	v_mul_f32_e32 v229, v6, v227
	v_mul_f32_e32 v2, v22, v227
	v_fmac_f32_e32 v229, v22, v226
	v_fma_f32 v228, v6, v226, -v2
	v_mul_f32_e32 v231, v6, v229
	v_mul_f32_e32 v2, v22, v229
	v_fmac_f32_e32 v231, v22, v228
	v_fma_f32 v230, v6, v228, -v2
	v_mul_f32_e32 v233, v18, v231
	v_mul_f32_e32 v2, v4, v231
	v_fmac_f32_e32 v233, v4, v230
	v_fma_f32 v232, v18, v230, -v2
	v_mul_f32_e32 v235, v6, v233
	v_mul_f32_e32 v2, v22, v233
	v_fmac_f32_e32 v235, v22, v232
	v_fma_f32 v234, v6, v232, -v2
	v_mul_f32_e32 v237, v6, v235
	v_mul_f32_e32 v2, v22, v235
	v_fmac_f32_e32 v237, v22, v234
	v_fma_f32 v236, v6, v234, -v2
	v_mul_f32_e32 v2, v22, v237
	v_mul_f32_e32 v179, v7, v175
	v_fma_f32 v238, v6, v236, -v2
	v_mul_f32_e32 v2, v3, v175
	v_fmac_f32_e32 v179, v3, v173
	v_fma_f32 v177, v7, v173, -v2
	v_mul_f32_e32 v241, v7, v179
	v_mul_f32_e32 v2, v3, v179
	v_fmac_f32_e32 v241, v3, v177
	v_fma_f32 v240, v7, v177, -v2
	v_mul_f32_e32 v243, v19, v241
	v_mul_f32_e32 v2, v5, v241
	v_fmac_f32_e32 v243, v5, v240
	v_fma_f32 v242, v19, v240, -v2
	v_mul_f32_e32 v245, v7, v243
	v_mul_f32_e32 v2, v3, v243
	v_fmac_f32_e32 v245, v3, v242
	v_fma_f32 v244, v7, v242, -v2
	v_mul_f32_e32 v247, v7, v245
	v_mul_f32_e32 v2, v3, v245
	v_fmac_f32_e32 v247, v3, v244
	v_fma_f32 v246, v7, v244, -v2
	v_mul_f32_e32 v249, v7, v247
	v_mul_f32_e32 v2, v3, v247
	v_fmac_f32_e32 v249, v3, v246
	v_fma_f32 v248, v7, v246, -v2
	v_mul_f32_e32 v251, v19, v249
	v_mul_f32_e32 v2, v5, v249
	v_fmac_f32_e32 v251, v5, v248
	v_fma_f32 v250, v19, v248, -v2
	v_mul_f32_e32 v253, v7, v251
	v_mul_f32_e32 v2, v3, v251
	v_fmac_f32_e32 v253, v3, v250
	v_fma_f32 v252, v7, v250, -v2
	v_mul_f32_e32 v205, v7, v253
	v_mul_f32_e32 v2, v3, v253
	v_fmac_f32_e32 v205, v3, v252
	v_fma_f32 v254, v7, v252, -v2
	v_mul_f32_e32 v2, v3, v205
	v_mul_f32_e32 v196, v7, v205
	v_fma_f32 v194, v7, v254, -v2
	v_fmac_f32_e32 v196, v3, v254
	v_lshl_add_u64 v[2:3], s[26:27], 0, v[148:149]
	v_lshl_add_u64 v[2:3], v[2:3], 0, v[146:147]
	s_mul_i32 s28, s42, 0x4200
	s_mov_b64 s[100:101], 0x4c000
	v_mbcnt_lo_u32_b32 v202, -1, 0
	v_mbcnt_hi_u32_b32 v202, -1, v202
	v_lshl_add_u32 v202, v202, 4, s28
	s_mov_b32 m0, s28
	s_nop 0
	global_load_lds_dwordx4 v[2:3], off
	v_lshl_add_u64 v[2:3], v[2:3], 0, s[100:101]
	s_add_u32 s28, s28, 0x400
	s_mov_b32 m0, s28
	s_nop 0
	global_load_lds_dwordx4 v[2:3], off
	v_lshl_add_u64 v[2:3], v[2:3], 0, s[100:101]
	s_add_u32 s28, s28, 0x400
	s_mov_b32 m0, s28
	s_nop 0
	global_load_lds_dwordx4 v[2:3], off
	v_lshl_add_u64 v[2:3], v[2:3], 0, s[100:101]
	s_add_u32 s28, s28, 0x400
	s_mov_b32 m0, s28
	s_nop 0
	global_load_lds_dwordx4 v[2:3], off
	v_lshl_add_u64 v[2:3], v[2:3], 0, s[100:101]
	s_add_u32 s28, s28, 0x400
	s_mov_b32 m0, s28
	s_nop 0
	global_load_lds_dwordx4 v[2:3], off
	v_lshl_add_u64 v[2:3], v[2:3], 0, s[100:101]
	s_add_u32 s28, s28, 0x400
	s_mov_b32 m0, s28
	s_nop 0
	global_load_lds_dwordx4 v[2:3], off
	v_lshl_add_u64 v[2:3], v[2:3], 0, s[100:101]
	s_add_u32 s28, s28, 0x400
	s_mov_b32 m0, s28
	s_nop 0
	global_load_lds_dwordx4 v[2:3], off
	v_lshl_add_u64 v[2:3], v[2:3], 0, s[100:101]
	s_add_u32 s28, s28, 0x400
	s_mov_b32 m0, s28
	s_nop 0
	global_load_lds_dwordx4 v[2:3], off
	v_lshl_add_u64 v[2:3], v[2:3], 0, s[100:101]
	s_add_u32 s28, s28, 0x400
	s_mov_b32 m0, s28
	s_nop 0
	global_load_lds_dwordx4 v[2:3], off
	v_lshl_add_u64 v[2:3], v[2:3], 0, s[100:101]
	s_add_u32 s28, s28, 0x400
	s_mov_b32 m0, s28
	s_nop 0
	global_load_lds_dwordx4 v[2:3], off
	v_lshl_add_u64 v[2:3], v[2:3], 0, s[100:101]
	s_add_u32 s28, s28, 0x400
	s_mov_b32 m0, s28
	s_nop 0
	global_load_lds_dwordx4 v[2:3], off
	v_lshl_add_u64 v[2:3], v[2:3], 0, s[100:101]
	s_add_u32 s28, s28, 0x400
	s_mov_b32 m0, s28
	s_nop 0
	global_load_lds_dwordx4 v[2:3], off
	v_lshl_add_u64 v[2:3], v[2:3], 0, s[100:101]
	s_add_u32 s28, s28, 0x400
	s_mov_b32 m0, s28
	s_nop 0
	global_load_lds_dwordx4 v[2:3], off
	v_lshl_add_u64 v[2:3], v[2:3], 0, s[100:101]
	s_add_u32 s28, s28, 0x400
	s_mov_b32 m0, s28
	s_nop 0
	global_load_lds_dwordx4 v[2:3], off
	v_lshl_add_u64 v[2:3], v[2:3], 0, s[100:101]
	s_add_u32 s28, s28, 0x400
	s_mov_b32 m0, s28
	s_nop 0
	global_load_lds_dwordx4 v[2:3], off
	v_lshl_add_u64 v[2:3], v[2:3], 0, s[100:101]
	s_add_u32 s28, s28, 0x400
	s_mov_b32 m0, s28
	s_nop 0
	global_load_lds_dwordx4 v[2:3], off
	v_mul_f32_e32 v239, v6, v237
	v_fmac_f32_e32 v239, v22, v236
	s_mov_b64 s[28:29], 0
	v_mov_b32_e32 v151, v150
	v_mov_b32_e32 v186, v150
	v_mov_b32_e32 v187, v150
	s_waitcnt vmcnt(15)
	ds_read_b128 v[50:53], v202
	s_waitcnt lgkmcnt(0)
	s_branch .LBB0_299
; DI float shflx(float v, int mask, int lane) { return __int_as_float(__builtin_amdgcn_ds_bpermute((lane ^ mask) << 2, __float_as_int(v))); }
; #define MFMA32(a, b, c) __builtin_amdgcn_mfma_f32_32x32x16_bf16((a), (b), (c), 0, 0, 0)
; DI void mix_s5(WVP CP pp, int l, u16* __restrict__ proj, char* smem) {
;     ...
; #pragma unroll
;         for (int half = 0; half < 2; ++half) {
;           const f32x16 bre = MFMA32(au, bfrag[half], z), bim = MFMA32(au, bfrag[2 + half], z);
;           float sr = 0.f, si = 0.f;
; #pragma unroll
;           for (int i = 0; i < 16; ++i) { sr += wre[half][i] * bre[i] - wim[half][i] * bim[i]; si += wre[half][i] * bim[i] + wim[half][i] * bre[i]; }
;           sr += shflx(sr, 32, lane); si += shflx(si, 32, lane);
;           const float nr = l32r[half] * Hr[half] - l32i[half] * Hi[half] + sr, ni = l32r[half] * Hi[half] + l32i[half] * Hr[half] + si;
;           Hr[half] = nr; Hi[half] = ni;
;         }
.LBB0_298:
	v_mfma_f32_32x32x16_bf16 v[18:33], v[50:53], v[70:73], 0
	s_add_u32 s28, s28, 0x4c000
	s_addc_u32 s29, s29, 0
	s_cmp_eq_u32 s28, 0x4c0000
	v_mfma_f32_32x32x16_bf16 v[2:17], v[50:53], v[66:69], 0
	s_nop 7
	v_mul_f32_e32 v34, v239, v18
	v_mul_f32_e32 v18, v238, v18
	s_nop 1
	v_fmac_f32_e32 v18, v239, v2
	v_fma_f32 v34, v238, v2, -v34
	v_add_f32_e32 v2, 0, v18
	v_mul_f32_e32 v18, v237, v19
	v_mul_f32_e32 v19, v236, v19
	v_add_f32_e32 v34, 0, v34
	v_fma_f32 v18, v236, v3, -v18
	v_fmac_f32_e32 v19, v237, v3
	v_mul_f32_e32 v3, v235, v20
	v_add_f32_e32 v18, v18, v34
	v_fma_f32 v3, v234, v4, -v3
	v_add_f32_e32 v3, v3, v18
	v_mul_f32_e32 v18, v234, v20
	v_fmac_f32_e32 v18, v235, v4
	v_mul_f32_e32 v4, v233, v21
	v_fma_f32 v4, v232, v5, -v4
	v_add_f32_e32 v2, v19, v2
	v_add_f32_e32 v3, v4, v3
	v_mul_f32_e32 v4, v232, v21
	v_add_f32_e32 v2, v18, v2
	v_fmac_f32_e32 v4, v233, v5
	v_add_f32_e32 v2, v4, v2
	v_mul_f32_e32 v4, v231, v22
	v_fma_f32 v4, v230, v6, -v4
	v_add_f32_e32 v3, v4, v3
	v_mul_f32_e32 v4, v230, v22
	v_fmac_f32_e32 v4, v231, v6
	v_add_f32_e32 v2, v4, v2
	v_mul_f32_e32 v4, v229, v23
	v_fma_f32 v4, v228, v7, -v4
	v_add_f32_e32 v3, v4, v3
	v_mul_f32_e32 v4, v228, v23
	v_fmac_f32_e32 v4, v229, v7
	v_add_f32_e32 v2, v4, v2
	v_mul_f32_e32 v4, v227, v24
	v_fma_f32 v4, v226, v8, -v4
	v_add_f32_e32 v3, v4, v3
	v_mul_f32_e32 v4, v226, v24
	v_fmac_f32_e32 v4, v227, v8
	v_add_f32_e32 v2, v4, v2
	v_mul_f32_e32 v4, v225, v25
	v_mfma_f32_32x32x16_bf16 v[34:49], v[50:53], v[74:77], 0
	v_fma_f32 v4, v224, v9, -v4
	v_mul_f32_e32 v5, v223, v26
	v_add_f32_e32 v3, v4, v3
	v_fma_f32 v5, v222, v10, -v5
	v_add_f32_e32 v3, v5, v3
	v_mul_f32_e32 v5, v178, v27
	v_fma_f32 v5, v176, v11, -v5
	v_mfma_f32_32x32x16_bf16 v[50:65], v[50:53], v[78:81], 0
	v_add_f32_e32 v3, v5, v3
	v_mul_f32_e32 v5, v174, v28
	v_fma_f32 v5, v172, v12, -v5
	v_add_f32_e32 v18, v5, v3
	v_mul_f32_e32 v3, v170, v29
	v_fma_f32 v20, v168, v13, -v3
	v_mul_f32_e32 v4, v224, v25
	s_nop 4
	v_mul_f32_e32 v3, v196, v50
	v_fma_f32 v3, v194, v34, -v3
	v_mul_f32_e32 v7, v205, v51
	v_add_f32_e32 v3, 0, v3
	v_mul_f32_e32 v5, v194, v50
	v_fma_f32 v7, v254, v35, -v7
	v_fmac_f32_e32 v5, v196, v34
	v_add_f32_e32 v3, v7, v3
	v_mul_f32_e32 v7, v254, v51
	v_add_f32_e32 v5, 0, v5
	v_fmac_f32_e32 v7, v205, v35
	v_add_f32_e32 v5, v7, v5
	v_mul_f32_e32 v7, v253, v52
	v_fma_f32 v7, v252, v36, -v7
	v_add_f32_e32 v3, v7, v3
	v_mul_f32_e32 v7, v252, v52
	v_fmac_f32_e32 v7, v253, v36
	v_add_f32_e32 v5, v7, v5
	v_mul_f32_e32 v7, v251, v53
	v_fma_f32 v7, v250, v37, -v7
	v_add_f32_e32 v3, v7, v3
	v_mul_f32_e32 v7, v250, v53
	v_fmac_f32_e32 v7, v251, v37
	v_add_f32_e32 v5, v7, v5
	v_mul_f32_e32 v7, v249, v54
	v_fma_f32 v7, v248, v38, -v7
	v_add_f32_e32 v3, v7, v3
	v_mul_f32_e32 v7, v248, v54
	v_fmac_f32_e32 v7, v249, v38
	v_add_f32_e32 v5, v7, v5
	v_mul_f32_e32 v7, v247, v55
	v_fma_f32 v7, v246, v39, -v7
	v_add_f32_e32 v3, v7, v3
	v_mul_f32_e32 v7, v246, v55
	v_fmac_f32_e32 v7, v247, v39
	v_add_f32_e32 v5, v7, v5
	v_mul_f32_e32 v7, v245, v56
	v_fma_f32 v7, v244, v40, -v7
	v_add_f32_e32 v7, v7, v3
	v_mul_f32_e32 v3, v244, v56
	v_fmac_f32_e32 v3, v245, v40
	v_add_f32_e32 v3, v3, v5
	v_mul_f32_e32 v5, v243, v57
	v_fmac_f32_e32 v4, v225, v9
	v_fma_f32 v5, v242, v41, -v5
	v_mul_f32_e32 v9, v241, v58
	v_add_f32_e32 v7, v5, v7
	v_mul_f32_e32 v5, v242, v57
	v_fma_f32 v9, v240, v42, -v9
	v_mul_f32_e32 v6, v222, v26
	v_mul_f32_e32 v8, v223, v10
	v_fmac_f32_e32 v5, v243, v41
	v_add_f32_e32 v10, v9, v7
	v_mul_f32_e32 v7, v240, v58
	v_mul_f32_e32 v9, v241, v42
	v_pk_add_f32 v[2:3], v[4:5], v[2:3]
	v_pk_add_f32 v[4:5], v[8:9], v[6:7]
	v_mov_b32_e32 v58, v27
	v_mul_f32_e32 v19, v179, v59
	v_pk_add_f32 v[2:3], v[4:5], v[2:3]
	v_pk_mul_f32 v[4:5], v[176:177], v[58:59]
	v_mov_b32_e32 v42, v11
	v_fma_f32 v19, v177, v43, -v19
	v_pk_fma_f32 v[4:5], v[178:179], v[42:43], v[4:5]
	v_add_f32_e32 v10, v19, v10
	v_mul_f32_e32 v19, v175, v60
	v_pk_add_f32 v[2:3], v[4:5], v[2:3]
	v_mov_b32_e32 v4, v28
	v_mov_b32_e32 v5, v60
	v_fma_f32 v19, v173, v44, -v19
	v_pk_mul_f32 v[4:5], v[172:173], v[4:5]
	v_mov_b32_e32 v6, v12
	v_mov_b32_e32 v7, v44
	v_add_f32_e32 v19, v19, v10
	v_mul_f32_e32 v10, v171, v61
	v_pk_fma_f32 v[4:5], v[174:175], v[6:7], v[4:5]
	v_mov_b32_e32 v60, v29
	v_mul_f32_e32 v22, v164, v14
	v_mul_f32_e32 v24, v166, v30
	v_fma_f32 v21, v169, v45, -v10
	v_mul_f32_e32 v23, v165, v46
	v_mul_f32_e32 v25, v167, v62
	v_pk_add_f32 v[2:3], v[4:5], v[2:3]
	v_pk_mul_f32 v[4:5], v[168:169], v[60:61]
	v_mov_b32_e32 v44, v13
	v_pk_add_f32 v[18:19], v[20:21], v[18:19]
	v_pk_add_f32 v[20:21], v[22:23], v[24:25] neg_lo:[0,1] neg_hi:[0,1]
	v_mov_b32_e32 v22, v31
	v_pk_fma_f32 v[4:5], v[170:171], v[44:45], v[4:5]
	v_mov_b32_e32 v31, v62
	v_pk_add_f32 v[18:19], v[20:21], v[18:19]
	v_mov_b32_e32 v20, v15
	v_pk_add_f32 v[2:3], v[4:5], v[2:3]
	v_pk_mul_f32 v[4:5], v[164:165], v[30:31]
	v_mov_b32_e32 v15, v46
	v_mov_b32_e32 v23, v63
	v_pk_fma_f32 v[4:5], v[166:167], v[14:15], v[4:5]
	v_mov_b32_e32 v21, v47
	v_pk_mul_f32 v[24:25], v[162:163], v[22:23]
	v_pk_add_f32 v[2:3], v[4:5], v[2:3]
	v_pk_mul_f32 v[4:5], v[160:161], v[22:23]
	v_pk_fma_f32 v[24:25], v[160:161], v[20:21], v[24:25] neg_lo:[0,0,1] neg_hi:[0,0,1]
	v_mov_b32_e32 v34, v32
	v_mov_b32_e32 v35, v64
	v_pk_fma_f32 v[4:5], v[162:163], v[20:21], v[4:5]
	v_pk_add_f32 v[18:19], v[24:25], v[18:19]
	v_mov_b32_e32 v24, v16
	v_mov_b32_e32 v25, v48
	v_pk_add_f32 v[2:3], v[4:5], v[2:3]
	v_pk_mul_f32 v[4:5], v[156:157], v[34:35]
	v_pk_mul_f32 v[36:37], v[158:159], v[34:35]
	v_mov_b32_e32 v64, v33
	v_pk_fma_f32 v[4:5], v[158:159], v[24:25], v[4:5]
	v_pk_fma_f32 v[36:37], v[156:157], v[24:25], v[36:37] neg_lo:[0,0,1] neg_hi:[0,0,1]
	v_mov_b32_e32 v48, v17
	v_pk_mul_f32 v[16:17], v[154:155], v[64:65]
	v_pk_add_f32 v[2:3], v[4:5], v[2:3]
	v_pk_mul_f32 v[4:5], v[152:153], v[64:65]
	v_pk_add_f32 v[18:19], v[36:37], v[18:19]
	v_pk_fma_f32 v[16:17], v[152:153], v[48:49], v[16:17] neg_lo:[0,0,1] neg_hi:[0,0,1]
	v_pk_fma_f32 v[4:5], v[154:155], v[48:49], v[4:5]
	v_pk_add_f32 v[16:17], v[16:17], v[18:19]
	v_pk_add_f32 v[2:3], v[4:5], v[2:3]
	ds_bpermute_b32 v10, v121, v16
	ds_bpermute_b32 v11, v121, v17
	ds_bpermute_b32 v4, v121, v2
	ds_bpermute_b32 v5, v121, v3
	v_pk_mul_f32 v[6:7], v[182:183], v[150:151]
	v_pk_mul_f32 v[8:9], v[182:183], v[186:187]
	s_waitcnt lgkmcnt(2)
	v_pk_add_f32 v[10:11], v[16:17], v[10:11]
	v_pk_fma_f32 v[6:7], v[180:181], v[186:187], v[6:7] neg_lo:[0,0,1] neg_hi:[0,0,1]
	s_waitcnt lgkmcnt(0)
	v_pk_add_f32 v[2:3], v[2:3], v[4:5]
	v_pk_fma_f32 v[4:5], v[180:181], v[150:151], v[8:9]
	v_pk_add_f32 v[186:187], v[6:7], v[10:11]
	v_pk_add_f32 v[150:151], v[4:5], v[2:3]
	s_cmp_eq_u32 s28, 0x4c0000
	s_cbranch_scc1 .LBB0_301
	s_cmp_lt_u32 s28, 0x260000
	s_cbranch_scc1 .Lp0w_1
	s_cmp_lt_u32 s28, 0x390000
	s_cbranch_scc1 .Lp0w_2
	s_cmp_lt_u32 s28, 0x428000
	s_cbranch_scc1 .Lp0w_3
	s_cmp_lt_u32 s28, 0x474000
	s_cbranch_scc1 .Lp0w_4
	s_waitcnt vmcnt(0)
	s_branch .Lp0w_done
; DI float shflx(float v, int mask, int lane) { return __int_as_float(__builtin_amdgcn_ds_bpermute((lane ^ mask) << 2, __float_as_int(v))); }
; #define MFMA32(a, b, c) __builtin_amdgcn_mfma_f32_32x32x16_bf16((a), (b), (c), 0, 0, 0)
; DI void mix_s5(WVP CP pp, int l, u16* __restrict__ proj, char* smem) {
;     ...
;       for (int ch = 0; ch < 16; ++ch) {
;         const bf16x8 au = au_n;
;         if (ch + 1 < 16) au_n = *(const bf16x8*)(ub + (long)((ch + 1) * 32 + l31) * INW + 8 * h);
; #pragma unroll
;         for (int half = 0; half < 2; ++half) {
;           const f32x16 bre = MFMA32(au, bfrag[half], z), bim = MFMA32(au, bfrag[2 + half], z);
;           float sr = 0.f, si = 0.f;
; #pragma unroll
;           for (int i = 0; i < 16; ++i) { sr += wre[half][i] * bre[i] - wim[half][i] * bim[i]; si += wre[half][i] * bim[i] + wim[half][i] * bre[i]; }
;           sr += shflx(sr, 32, lane); si += shflx(si, 32, lane);
;           const float nr = l32r[half] * Hr[half] - l32i[half] * Hi[half] + sr, ni = l32r[half] * Hi[half] + l32i[half] * Hr[half] + si;
;           Hr[half] = nr; Hi[half] = ni;
;         }
;       }
;       if (h == 0) {
;         hend[wave * 128 + l31] = Hr[0]; hend[wave * 128 + 64 + l31] = Hi[0];
;         hend[wave * 128 + 32 + l31] = Hr[1]; hend[wave * 128 + 96 + l31] = Hi[1];
;       }
.Lp0w_4:
	s_waitcnt vmcnt(1)
	s_branch .Lp0w_done
.Lp0w_3:
	s_cmp_lt_u32 s28, 0x3dc000
	s_cbranch_scc1 .Lp0w_5
	s_waitcnt vmcnt(2)
	s_branch .Lp0w_done
.Lp0w_5:
	s_waitcnt vmcnt(3)
	s_branch .Lp0w_done
.Lp0w_2:
	s_cmp_lt_u32 s28, 0x2f8000
	s_cbranch_scc1 .Lp0w_6
	s_cmp_lt_u32 s28, 0x344000
	s_cbranch_scc1 .Lp0w_7
	s_waitcnt vmcnt(4)
	s_branch .Lp0w_done
.Lp0w_7:
	s_waitcnt vmcnt(5)
	s_branch .Lp0w_done
.Lp0w_6:
	s_cmp_lt_u32 s28, 0x2ac000
	s_cbranch_scc1 .Lp0w_8
	s_waitcnt vmcnt(6)
	s_branch .Lp0w_done
.Lp0w_8:
	s_waitcnt vmcnt(7)
	s_branch .Lp0w_done
.Lp0w_1:
	s_cmp_lt_u32 s28, 0x130000
	s_cbranch_scc1 .Lp0w_9
	s_cmp_lt_u32 s28, 0x1c8000
	s_cbranch_scc1 .Lp0w_10
	s_cmp_lt_u32 s28, 0x214000
	s_cbranch_scc1 .Lp0w_11
	s_waitcnt vmcnt(8)
	s_branch .Lp0w_done
.Lp0w_11:
	s_waitcnt vmcnt(9)
	s_branch .Lp0w_done
.Lp0w_10:
	s_cmp_lt_u32 s28, 0x17c000
	s_cbranch_scc1 .Lp0w_12
	s_waitcnt vmcnt(10)
	s_branch .Lp0w_done
.Lp0w_12:
	s_waitcnt vmcnt(11)
	s_branch .Lp0w_done
.Lp0w_9:
	s_cmp_lt_u32 s28, 0x98000
	s_cbranch_scc1 .Lp0w_13
	s_cmp_lt_u32 s28, 0xe4000
	s_cbranch_scc1 .Lp0w_14
	s_waitcnt vmcnt(12)
	s_branch .Lp0w_done
.Lp0w_14:
	s_waitcnt vmcnt(13)
	s_branch .Lp0w_done
.Lp0w_13:
	s_waitcnt vmcnt(14)
	s_branch .Lp0w_done
.Lp0w_done:
	v_add_u32_e32 v202, 0x400, v202
	ds_read_b128 v[50:53], v202
	s_waitcnt lgkmcnt(0)
.LBB0_299:
	s_branch .LBB0_298
.LBB0_301:
	s_and_saveexec_b64 s[28:29], s[8:9]
	s_cbranch_execz .LBB0_303
	ds_write_b32 v215, v150 offset:256
	ds_write2_b32 v215, v186, v187 offset1:32
	ds_write_b32 v215, v151 offset:384
